# input-projection epilogue: row sum-of-squares loads hoisted out of the 8 row groups into one batched cooperative load
# speedup vs baseline: 1.0328x; 1.0215x over previous
; template <int N4> __device__ __forceinline__ float sum_parts(const float* p) {
;     f32x4 a = *(const f32x4*)p;
; #pragma unroll
;     for (int i = 1; i < N4; ++i) a += *(const f32x4*)(p + 4 * i);
;     return (a[0] + a[1]) + (a[2] + a[3]);
; }
;     __device__ __forceinline__ void operator()(const f32x4 (&acc)[2][2][4][2], const Unit& u, int wr, int wc, int fr, int fq) const {
;     ...
; #pragma unroll
;         for (int ai = 0; ai < 2; ++ai)
; #pragma unroll
;             for (int m = 0; m < 4; ++m) {
;                 const int row = row0 + ai * HALF + m * 16;
;                 const float r = __builtin_amdgcn_rsqf(sum_parts<8>(ssq_h + (size_t)row * 32) * (1.0f / 2048.0f) + 1e-6f);
; #pragma unroll
;                 for (int bj = 0; bj < 2; ++bj) {
;                     float v[8];
; #pragma unroll
;                     for (int e = 0; e < 4; ++e) { v[e] = acc[ai][bj][m][0][e] * r; v[4 + e] = acc[ai][bj][m][1][e] * r; }
;                     if (tab[bj] >= 0) rope8(v, TAB + (size_t)row * NTAB + tab[bj]);
.LBB0_343:
	s_ashr_i32 s1, s1, 2
	s_andn2_b32 s1, s1, 63
	v_lshrrev_b32_e32 v198, 4, v146
	v_and_or_b32 v146, v146, 15, s1
	v_lshl_add_u32 v146, s87, 8, v146
	v_ashrrev_i32_e32 v147, 31, v146
	v_lshlrev_b32_e32 v198, 5, v198
	v_mov_b32_e32 v199, 0
	v_lshlrev_b64 v[190:191], 7, v[146:147]
	v_lshl_add_u64 v[190:191], s[22:23], 0, v[190:191]
	v_lshl_add_u64 v[190:191], v[190:191], 0, v[198:199]
	v_mov_b32_e32 v160, 0x1000
	v_mov_b32_e32 v161, 0
	v_lshl_add_u64 v[192:193], v[160:161], 0, v[190:191]
	v_lshl_add_u64 v[194:195], v[160:161], 2, v[190:191]
	v_lshl_add_u64 v[196:197], v[160:161], 0, v[194:195]
	global_load_dwordx4 v[218:221], v[190:191], off
	global_load_dwordx4 v[222:225], v[190:191], off offset:16
	global_load_dwordx4 v[226:229], v[190:191], off offset:2048
	global_load_dwordx4 v[230:233], v[190:191], off offset:2064
	global_load_dwordx4 v[234:237], v[192:193], off
	global_load_dwordx4 v[238:241], v[192:193], off offset:16
	global_load_dwordx4 v[178:181], v[192:193], off offset:2048
	global_load_dwordx4 v[182:185], v[192:193], off offset:2064
	global_load_dwordx4 v[186:189], v[194:195], off
	global_load_dwordx4 v[154:157], v[194:195], off offset:16
	global_load_dwordx4 v[160:163], v[194:195], off offset:2048
	global_load_dwordx4 v[164:167], v[194:195], off offset:2064
	s_waitcnt vmcnt(0)
	v_pk_add_f32 v[218:219], v[218:219], v[220:221]
	v_pk_add_f32 v[222:223], v[222:223], v[224:225]
	v_pk_add_f32 v[218:219], v[218:219], v[222:223]
	v_add_f32_e32 v168, v218, v219
	v_pk_add_f32 v[226:227], v[226:227], v[228:229]
	v_pk_add_f32 v[230:231], v[230:231], v[232:233]
	v_pk_add_f32 v[226:227], v[226:227], v[230:231]
	v_add_f32_e32 v169, v226, v227
	v_pk_add_f32 v[234:235], v[234:235], v[236:237]
	v_pk_add_f32 v[238:239], v[238:239], v[240:241]
	v_pk_add_f32 v[234:235], v[234:235], v[238:239]
	v_add_f32_e32 v170, v234, v235
	v_pk_add_f32 v[178:179], v[178:179], v[180:181]
	v_pk_add_f32 v[182:183], v[182:183], v[184:185]
	v_pk_add_f32 v[178:179], v[178:179], v[182:183]
	v_add_f32_e32 v171, v178, v179
	v_pk_add_f32 v[186:187], v[186:187], v[188:189]
	v_pk_add_f32 v[154:155], v[154:155], v[156:157]
	v_pk_add_f32 v[186:187], v[186:187], v[154:155]
	v_add_f32_e32 v172, v186, v187
	v_pk_add_f32 v[160:161], v[160:161], v[162:163]
	v_pk_add_f32 v[164:165], v[164:165], v[166:167]
	v_pk_add_f32 v[160:161], v[160:161], v[164:165]
	v_add_f32_e32 v173, v160, v161
	global_load_dwordx4 v[218:221], v[196:197], off
	global_load_dwordx4 v[222:225], v[196:197], off offset:16
	global_load_dwordx4 v[226:229], v[196:197], off offset:2048
	global_load_dwordx4 v[230:233], v[196:197], off offset:2064
	s_waitcnt vmcnt(0)
	v_pk_add_f32 v[218:219], v[218:219], v[220:221]
	v_pk_add_f32 v[222:223], v[222:223], v[224:225]
	v_pk_add_f32 v[218:219], v[218:219], v[222:223]
	v_add_f32_e32 v174, v218, v219
	v_pk_add_f32 v[226:227], v[226:227], v[228:229]
	v_pk_add_f32 v[230:231], v[230:231], v[232:233]
	v_pk_add_f32 v[226:227], v[226:227], v[230:231]
	v_add_f32_e32 v175, v226, v227
	v_mov_b32_e32 v234, v168
	v_mov_b32_e32 v235, v169
	v_mov_b32_e32 v236, v170
	v_mov_b32_e32 v237, v171
	v_mov_b32_e32 v238, v172
	v_mov_b32_e32 v239, v173
	v_mov_b32_e32 v240, v174
	v_mov_b32_e32 v241, v175
	v_permlane32_swap_b32_e32 v168, v234
	v_permlane32_swap_b32_e32 v169, v235
	v_permlane32_swap_b32_e32 v170, v236
	v_permlane32_swap_b32_e32 v171, v237
	v_permlane32_swap_b32_e32 v172, v238
	v_permlane32_swap_b32_e32 v173, v239
	v_permlane32_swap_b32_e32 v174, v240
	v_permlane32_swap_b32_e32 v175, v241
	v_add_f32_e32 v168, v168, v234
	v_add_f32_e32 v169, v169, v235
	v_add_f32_e32 v170, v170, v236
	v_add_f32_e32 v171, v171, v237
	v_add_f32_e32 v172, v172, v238
	v_add_f32_e32 v173, v173, v239
	v_add_f32_e32 v174, v174, v240
	v_add_f32_e32 v175, v175, v241
	v_mov_b32_e32 v234, v168
	v_mov_b32_e32 v235, v169
	v_mov_b32_e32 v236, v170
	v_mov_b32_e32 v237, v171
	v_mov_b32_e32 v238, v172
	v_mov_b32_e32 v239, v173
	v_mov_b32_e32 v240, v174
	v_mov_b32_e32 v241, v175
	v_permlane16_swap_b32_e32 v168, v234
	v_permlane16_swap_b32_e32 v169, v235
	v_permlane16_swap_b32_e32 v170, v236
	v_permlane16_swap_b32_e32 v171, v237
	v_permlane16_swap_b32_e32 v172, v238
	v_permlane16_swap_b32_e32 v173, v239
	v_permlane16_swap_b32_e32 v174, v240
	v_permlane16_swap_b32_e32 v175, v241
	v_add_f32_e32 v168, v168, v234
	v_add_f32_e32 v169, v169, v235
	v_add_f32_e32 v170, v170, v236
	v_add_f32_e32 v171, v171, v237
	v_add_f32_e32 v172, v172, v238
	v_add_f32_e32 v173, v173, v239
	v_add_f32_e32 v174, v174, v240
	v_add_f32_e32 v175, v175, v241
	v_fmamk_f32 v168, v168, 0x3a000000, v204
	v_fmamk_f32 v169, v169, 0x3a000000, v204
	v_fmamk_f32 v170, v170, 0x3a000000, v204
	v_fmamk_f32 v171, v171, 0x3a000000, v204
	v_fmamk_f32 v172, v172, 0x3a000000, v204
	v_fmamk_f32 v173, v173, 0x3a000000, v204
	v_fmamk_f32 v174, v174, 0x3a000000, v204
	v_fmamk_f32 v175, v175, 0x3a000000, v204
	v_rsq_f32_e32 v168, v168
	v_rsq_f32_e32 v169, v169
	v_rsq_f32_e32 v170, v170
	v_rsq_f32_e32 v171, v171
	v_rsq_f32_e32 v172, v172
	v_rsq_f32_e32 v173, v173
	v_rsq_f32_e32 v174, v174
	v_rsq_f32_e32 v175, v175
	s_movk_i32 s1, 0x1c0
	v_mad_i64_i32 v[156:157], s[6:7], v146, s1, 0
	v_mov_b32_e32 v154, v168
	v_cmp_lt_i32_e64 s[6:7], -1, v0
	v_lshl_add_u64 v[156:157], s[70:71], 0, v[156:157]
	v_pk_mul_f32 v[2:3], v[2:3], v[154:155] op_sel_hi:[1,0]
	v_pk_mul_f32 v[6:7], v[6:7], v[154:155] op_sel_hi:[1,0]
	v_pk_mul_f32 v[4:5], v[4:5], v[154:155] op_sel_hi:[1,0]
	v_pk_mul_f32 v[8:9], v[8:9], v[154:155] op_sel_hi:[1,0]
	s_and_saveexec_b64 s[8:9], s[6:7]
	s_cbranch_execz .LBB0_345
	v_lshl_add_u64 v[160:161], v[0:1], 3, v[156:157]
	global_load_dwordx4 v[184:187], v[160:161], off offset:16
	global_load_dwordx4 v[180:183], v[160:161], off
	s_waitcnt vmcnt(0)
	v_pk_mul_f32 v[160:161], v[2:3], v[180:181] op_sel:[1,1] op_sel_hi:[1,0]
	s_nop 0
	v_pk_fma_f32 v[178:179], v[2:3], v[180:181], v[160:161] op_sel_hi:[0,1,1] neg_lo:[0,0,1] neg_hi:[0,0,1]
	v_pk_fma_f32 v[2:3], v[2:3], v[180:181], v[160:161] op_sel_hi:[0,1,1]
	v_pk_mul_f32 v[160:161], v[4:5], v[182:183] op_sel:[1,1] op_sel_hi:[1,0]
	v_mul_f32_e32 v2, v9, v187
	v_pk_fma_f32 v[180:181], v[4:5], v[182:183], v[160:161] op_sel_hi:[0,1,1] neg_lo:[0,0,1] neg_hi:[0,0,1]
	v_pk_fma_f32 v[4:5], v[4:5], v[182:183], v[160:161] op_sel_hi:[0,1,1]
	v_pk_mul_f32 v[160:161], v[6:7], v[184:185] op_sel:[1,1] op_sel_hi:[1,0]
	v_mov_b32_e32 v179, v3
	v_pk_fma_f32 v[182:183], v[6:7], v[184:185], v[160:161] op_sel_hi:[0,1,1] neg_lo:[0,0,1] neg_hi:[0,0,1]
	v_pk_fma_f32 v[6:7], v[6:7], v[184:185], v[160:161] op_sel_hi:[0,1,1]
	v_pk_fma_f32 v[184:185], v[8:9], v[186:187], v[2:3] op_sel_hi:[1,1,0] neg_lo:[0,0,1] neg_hi:[0,0,1]
	v_mul_f32_e32 v2, v9, v186
	v_pk_fma_f32 v[8:9], v[8:9], v[186:187], v[2:3] op_sel:[0,1,0] op_sel_hi:[1,0,0]
	v_mov_b32_e32 v181, v5
	v_mov_b32_e32 v183, v7
	v_mov_b32_e32 v185, v8
	v_mov_b64_e32 v[2:3], v[178:179]
	v_mov_b64_e32 v[4:5], v[180:181]
	v_mov_b64_e32 v[6:7], v[182:183]
	v_mov_b64_e32 v[8:9], v[184:185]

;     __device__ __forceinline__ void operator()(const f32x4 (&acc)[2][2][4][2], const Unit& u, int wr, int wc, int fr, int fq) const {
;     ...
; #pragma unroll
;         for (int ai = 0; ai < 2; ++ai)
; #pragma unroll
;             for (int m = 0; m < 4; ++m) {
;                 const int row = row0 + ai * HALF + m * 16;
;                 const float r = __builtin_amdgcn_rsqf(sum_parts<8>(ssq_h + (size_t)row * 32) * (1.0f / 2048.0f) + 1e-6f);
; #pragma unroll
;                 for (int bj = 0; bj < 2; ++bj) {
;                     float v[8];
; #pragma unroll
;                     for (int e = 0; e < 4; ++e) { v[e] = acc[ai][bj][m][0][e] * r; v[4 + e] = acc[ai][bj][m][1][e] * r; }
;                     if (tab[bj] >= 0) rope8(v, TAB + (size_t)row * NTAB + tab[bj]);
.LBB0_359:
	v_ashrrev_i32_e32 v151, 31, v150
	v_mul_lo_u32 v8, s93, v146
	v_mul_lo_u32 v9, s92, v147
	s_waitcnt lgkmcnt(0)
	v_mad_u64_u32 v[6:7], s[14:15], s92, v146, 0
	v_lshl_add_u64 v[122:123], v[150:151], 1, v[152:153]
	v_add3_u32 v7, v7, v9, v8
	v_lshl_add_u64 v[128:129], v[6:7], 1, v[122:123]
	v_cvt_pk_bf16_f32 v6, v125, v127
	v_cvt_pk_bf16_f32 v7, v124, v126
	v_or_b32_e32 v124, 16, v146
	v_ashrrev_i32_e32 v125, 31, v124
	v_cvt_pk_bf16_f32 v8, v3, v5
	v_cvt_pk_bf16_f32 v9, v2, v4
	global_store_dwordx4 v[128:129], v[6:9], off
	v_mad_i64_i32 v[128:129], s[14:15], v124, s1, 0
	v_mov_b32_e32 v126, v169
	s_nop 0
	v_pk_mul_f32 v[2:3], v[118:119], v[126:127] op_sel_hi:[1,0]
	v_pk_mul_f32 v[6:7], v[114:115], v[126:127] op_sel_hi:[1,0]
	v_pk_mul_f32 v[4:5], v[120:121], v[126:127] op_sel_hi:[1,0]
	v_pk_mul_f32 v[8:9], v[116:117], v[126:127] op_sel_hi:[1,0]
	v_lshl_add_u64 v[114:115], s[70:71], 0, v[128:129]
	s_and_saveexec_b64 s[14:15], s[6:7]
	s_cbranch_execz .LBB0_361
	v_lshl_add_u64 v[120:121], v[0:1], 3, v[114:115]
	global_load_dwordx4 v[116:119], v[120:121], off offset:16
	global_load_dwordx4 v[152:155], v[120:121], off
	s_waitcnt vmcnt(0)
	v_pk_mul_f32 v[120:121], v[2:3], v[152:153] op_sel:[1,1] op_sel_hi:[1,0]
	s_nop 0
	v_pk_fma_f32 v[150:151], v[2:3], v[152:153], v[120:121] op_sel_hi:[0,1,1] neg_lo:[0,0,1] neg_hi:[0,0,1]
	v_pk_fma_f32 v[2:3], v[2:3], v[152:153], v[120:121] op_sel_hi:[0,1,1]
	v_pk_mul_f32 v[120:121], v[4:5], v[154:155] op_sel:[1,1] op_sel_hi:[1,0]
	v_mul_f32_e32 v2, v9, v119
	v_pk_fma_f32 v[152:153], v[4:5], v[154:155], v[120:121] op_sel_hi:[0,1,1] neg_lo:[0,0,1] neg_hi:[0,0,1]
	v_pk_fma_f32 v[4:5], v[4:5], v[154:155], v[120:121] op_sel_hi:[0,1,1]
	v_pk_mul_f32 v[120:121], v[6:7], v[116:117] op_sel:[1,1] op_sel_hi:[1,0]
	v_pk_fma_f32 v[156:157], v[8:9], v[118:119], v[2:3] op_sel_hi:[1,1,0] neg_lo:[0,0,1] neg_hi:[0,0,1]
	v_mul_f32_e32 v2, v9, v118
	v_pk_fma_f32 v[154:155], v[6:7], v[116:117], v[120:121] op_sel_hi:[0,1,1] neg_lo:[0,0,1] neg_hi:[0,0,1]
	v_pk_fma_f32 v[6:7], v[6:7], v[116:117], v[120:121] op_sel_hi:[0,1,1]
	v_pk_fma_f32 v[8:9], v[8:9], v[118:119], v[2:3] op_sel:[0,1,0] op_sel_hi:[1,0,0]
	v_mov_b32_e32 v151, v3
	v_mov_b32_e32 v153, v5
	v_mov_b32_e32 v155, v7
	v_mov_b32_e32 v157, v8
	v_mov_b64_e32 v[2:3], v[150:151]
	v_mov_b64_e32 v[4:5], v[152:153]
	v_mov_b64_e32 v[6:7], v[154:155]
	v_mov_b64_e32 v[8:9], v[156:157]

;     __device__ __forceinline__ void operator()(const f32x4 (&acc)[2][2][4][2], const Unit& u, int wr, int wc, int fr, int fq) const {
;     ...
; #pragma unroll
;         for (int ai = 0; ai < 2; ++ai)
; #pragma unroll
;             for (int m = 0; m < 4; ++m) {
;                 const int row = row0 + ai * HALF + m * 16;
;                 const float r = __builtin_amdgcn_rsqf(sum_parts<8>(ssq_h + (size_t)row * 32) * (1.0f / 2048.0f) + 1e-6f);
; #pragma unroll
;                 for (int bj = 0; bj < 2; ++bj) {
;                     float v[8];
; #pragma unroll
;                     for (int e = 0; e < 4; ++e) { v[e] = acc[ai][bj][m][0][e] * r; v[4 + e] = acc[ai][bj][m][1][e] * r; }
;                     if (tab[bj] >= 0) rope8(v, TAB + (size_t)row * NTAB + tab[bj]);
.LBB0_375:
	v_mul_lo_u32 v7, s93, v124
	v_mul_lo_u32 v109, s92, v125
	s_waitcnt lgkmcnt(0)
	v_mad_u64_u32 v[8:9], s[18:19], s92, v124, 0
	v_add3_u32 v9, v9, v109, v7
	v_lshl_add_u64 v[8:9], v[8:9], 1, v[122:123]
	v_cvt_pk_bf16_f32 v106, v106, v108
	v_cvt_pk_bf16_f32 v107, v4, v107
	v_cvt_pk_bf16_f32 v108, v3, v5
	v_cvt_pk_bf16_f32 v109, v2, v6
	global_store_dwordx4 v[8:9], v[106:109], off
	s_nop 1
	v_or_b32_e32 v106, 32, v146
	v_ashrrev_i32_e32 v107, 31, v106
	v_mad_i64_i32 v[110:111], s[18:19], v106, s1, 0
	v_mov_b32_e32 v108, v170
	s_nop 0
	v_pk_mul_f32 v[2:3], v[102:103], v[108:109] op_sel_hi:[1,0]
	v_pk_mul_f32 v[6:7], v[98:99], v[108:109] op_sel_hi:[1,0]
	v_pk_mul_f32 v[4:5], v[104:105], v[108:109] op_sel_hi:[1,0]
	v_pk_mul_f32 v[8:9], v[100:101], v[108:109] op_sel_hi:[1,0]
	v_lshl_add_u64 v[98:99], s[70:71], 0, v[110:111]
	s_and_saveexec_b64 s[18:19], s[6:7]
	s_cbranch_execz .LBB0_377
	v_lshl_add_u64 v[104:105], v[0:1], 3, v[98:99]
	global_load_dwordx4 v[100:103], v[104:105], off offset:16
	global_load_dwordx4 v[112:115], v[104:105], off
	s_waitcnt vmcnt(0)
	v_pk_mul_f32 v[104:105], v[2:3], v[112:113] op_sel:[1,1] op_sel_hi:[1,0]
	s_nop 0
	v_pk_fma_f32 v[110:111], v[2:3], v[112:113], v[104:105] op_sel_hi:[0,1,1] neg_lo:[0,0,1] neg_hi:[0,0,1]
	v_pk_fma_f32 v[2:3], v[2:3], v[112:113], v[104:105] op_sel_hi:[0,1,1]
	v_pk_mul_f32 v[104:105], v[4:5], v[114:115] op_sel:[1,1] op_sel_hi:[1,0]
	v_mul_f32_e32 v2, v9, v103
	v_pk_fma_f32 v[112:113], v[4:5], v[114:115], v[104:105] op_sel_hi:[0,1,1] neg_lo:[0,0,1] neg_hi:[0,0,1]
	v_pk_fma_f32 v[4:5], v[4:5], v[114:115], v[104:105] op_sel_hi:[0,1,1]
	v_pk_mul_f32 v[104:105], v[6:7], v[100:101] op_sel:[1,1] op_sel_hi:[1,0]
	v_pk_fma_f32 v[116:117], v[8:9], v[102:103], v[2:3] op_sel_hi:[1,1,0] neg_lo:[0,0,1] neg_hi:[0,0,1]
	v_mul_f32_e32 v2, v9, v102
	v_pk_fma_f32 v[114:115], v[6:7], v[100:101], v[104:105] op_sel_hi:[0,1,1] neg_lo:[0,0,1] neg_hi:[0,0,1]
	v_pk_fma_f32 v[6:7], v[6:7], v[100:101], v[104:105] op_sel_hi:[0,1,1]
	v_pk_fma_f32 v[8:9], v[8:9], v[102:103], v[2:3] op_sel:[0,1,0] op_sel_hi:[1,0,0]
	v_mov_b32_e32 v111, v3
	v_mov_b32_e32 v113, v5
	v_mov_b32_e32 v115, v7
	v_mov_b32_e32 v117, v8
	v_mov_b64_e32 v[2:3], v[110:111]
	v_mov_b64_e32 v[4:5], v[112:113]
	v_mov_b64_e32 v[6:7], v[114:115]
	v_mov_b64_e32 v[8:9], v[116:117]

;     __device__ __forceinline__ void operator()(const f32x4 (&acc)[2][2][4][2], const Unit& u, int wr, int wc, int fr, int fq) const {
;     ...
; #pragma unroll
;         for (int ai = 0; ai < 2; ++ai)
; #pragma unroll
;             for (int m = 0; m < 4; ++m) {
;                 const int row = row0 + ai * HALF + m * 16;
;                 const float r = __builtin_amdgcn_rsqf(sum_parts<8>(ssq_h + (size_t)row * 32) * (1.0f / 2048.0f) + 1e-6f);
; #pragma unroll
;                 for (int bj = 0; bj < 2; ++bj) {
;                     float v[8];
; #pragma unroll
;                     for (int e = 0; e < 4; ++e) { v[e] = acc[ai][bj][m][0][e] * r; v[4 + e] = acc[ai][bj][m][1][e] * r; }
;                     if (tab[bj] >= 0) rope8(v, TAB + (size_t)row * NTAB + tab[bj]);
.LBB0_391:
	v_mul_lo_u32 v7, s93, v106
	v_mul_lo_u32 v93, s92, v107
	s_waitcnt lgkmcnt(0)
	v_mad_u64_u32 v[8:9], s[18:19], s92, v106, 0
	v_add3_u32 v9, v9, v93, v7
	v_lshl_add_u64 v[8:9], v[8:9], 1, v[122:123]
	v_cvt_pk_bf16_f32 v90, v90, v92
	v_cvt_pk_bf16_f32 v91, v4, v91
	v_cvt_pk_bf16_f32 v92, v3, v5
	v_cvt_pk_bf16_f32 v93, v2, v6
	global_store_dwordx4 v[8:9], v[90:93], off
	s_nop 1
	v_or_b32_e32 v90, 48, v146
	v_ashrrev_i32_e32 v91, 31, v90
	v_mad_i64_i32 v[94:95], s[18:19], v90, s1, 0
	v_mov_b32_e32 v92, v171
	s_nop 0
	v_pk_mul_f32 v[2:3], v[86:87], v[92:93] op_sel_hi:[1,0]
	v_pk_mul_f32 v[6:7], v[82:83], v[92:93] op_sel_hi:[1,0]
	v_pk_mul_f32 v[4:5], v[88:89], v[92:93] op_sel_hi:[1,0]
	v_pk_mul_f32 v[8:9], v[84:85], v[92:93] op_sel_hi:[1,0]
	v_lshl_add_u64 v[82:83], s[70:71], 0, v[94:95]
	s_and_saveexec_b64 s[18:19], s[6:7]
	s_cbranch_execz .LBB0_393
	v_lshl_add_u64 v[88:89], v[0:1], 3, v[82:83]
	global_load_dwordx4 v[84:87], v[88:89], off offset:16
	global_load_dwordx4 v[96:99], v[88:89], off
	s_waitcnt vmcnt(0)
	v_pk_mul_f32 v[88:89], v[2:3], v[96:97] op_sel:[1,1] op_sel_hi:[1,0]
	s_nop 0
	v_pk_fma_f32 v[94:95], v[2:3], v[96:97], v[88:89] op_sel_hi:[0,1,1] neg_lo:[0,0,1] neg_hi:[0,0,1]
	v_pk_fma_f32 v[2:3], v[2:3], v[96:97], v[88:89] op_sel_hi:[0,1,1]
	v_pk_mul_f32 v[88:89], v[4:5], v[98:99] op_sel:[1,1] op_sel_hi:[1,0]
	v_mul_f32_e32 v2, v9, v87
	v_pk_fma_f32 v[96:97], v[4:5], v[98:99], v[88:89] op_sel_hi:[0,1,1] neg_lo:[0,0,1] neg_hi:[0,0,1]
	v_pk_fma_f32 v[4:5], v[4:5], v[98:99], v[88:89] op_sel_hi:[0,1,1]
	v_pk_mul_f32 v[88:89], v[6:7], v[84:85] op_sel:[1,1] op_sel_hi:[1,0]
	v_pk_fma_f32 v[100:101], v[8:9], v[86:87], v[2:3] op_sel_hi:[1,1,0] neg_lo:[0,0,1] neg_hi:[0,0,1]
	v_mul_f32_e32 v2, v9, v86
	v_pk_fma_f32 v[98:99], v[6:7], v[84:85], v[88:89] op_sel_hi:[0,1,1] neg_lo:[0,0,1] neg_hi:[0,0,1]
	v_pk_fma_f32 v[6:7], v[6:7], v[84:85], v[88:89] op_sel_hi:[0,1,1]
	v_pk_fma_f32 v[8:9], v[8:9], v[86:87], v[2:3] op_sel:[0,1,0] op_sel_hi:[1,0,0]
	v_mov_b32_e32 v95, v3
	v_mov_b32_e32 v97, v5
	v_mov_b32_e32 v99, v7
	v_mov_b32_e32 v101, v8
	v_mov_b64_e32 v[2:3], v[94:95]
	v_mov_b64_e32 v[4:5], v[96:97]
	v_mov_b64_e32 v[6:7], v[98:99]
	v_mov_b64_e32 v[8:9], v[100:101]

; __device__ __forceinline__ float silu_f(float x) { return x * __builtin_amdgcn_rcpf(1.0f + __builtin_amdgcn_exp2f(-x * 1.4426950408889634f)); }
;     __device__ __forceinline__ void operator()(const f32x4 (&acc)[2][2][4][2], const Unit& u, int wr, int wc, int fr, int fq) const {
;     ...
;                 const int row = row0 + ai * HALF + m * 16;
;                 const float r = __builtin_amdgcn_rsqf(sum_parts<8>(ssq_h + (size_t)row * 32) * (1.0f / 2048.0f) + 1e-6f);
; #pragma unroll
;                 for (int bj = 0; bj < 2; ++bj) {
;                     float v[8];
; #pragma unroll
;                     for (int e = 0; e < 4; ++e) { v[e] = acc[ai][bj][m][0][e] * r; v[4 + e] = acc[ai][bj][m][1][e] * r; }
;                     if (tab[bj] >= 0) rope8(v, TAB + (size_t)row * NTAB + tab[bj]);
;                     if (act[bj]) {
; #pragma unroll
;                         for (int e = 0; e < 8; ++e) v[e] = silu_f(v[e]);
;                     }
; #pragma unroll
;                     for (int e = 0; e < 8; ++e) v[e] *= sc[bj];
;                     if (ssq[bj]) { float s = 0.f;
; #pragma unroll
;                         for (int e = 0; e < 8; ++e) s += v[e] * v[e];
;                         s += __shfl_xor(s, 16); s += __shfl_xor(s, 32);
;                         if (fq == 0) ssq[bj][(size_t)row * sld[bj]] = s; }
;                     store8(dst[bj] + (size_t)row * ld[bj], v);
.LBB0_407:
	v_mul_lo_u32 v7, s93, v90
	v_mul_lo_u32 v77, s92, v91
	s_waitcnt lgkmcnt(0)
	v_mad_u64_u32 v[8:9], s[18:19], s92, v90, 0
	v_add3_u32 v9, v9, v77, v7
	v_lshl_add_u64 v[8:9], v[8:9], 1, v[122:123]
	v_cvt_pk_bf16_f32 v74, v74, v76
	v_cvt_pk_bf16_f32 v75, v4, v75
	v_cvt_pk_bf16_f32 v76, v3, v5
	v_cvt_pk_bf16_f32 v77, v2, v6
	global_store_dwordx4 v[8:9], v[74:77], off
	s_nop 1
	v_add_u32_e32 v74, 0x80, v146
	v_ashrrev_i32_e32 v75, 31, v74
	v_mad_i64_i32 v[78:79], s[18:19], v74, s1, 0
	v_mov_b32_e32 v76, v172
	s_nop 0
	v_pk_mul_f32 v[2:3], v[70:71], v[76:77] op_sel_hi:[1,0]
	v_pk_mul_f32 v[6:7], v[66:67], v[76:77] op_sel_hi:[1,0]
	v_pk_mul_f32 v[4:5], v[72:73], v[76:77] op_sel_hi:[1,0]
	v_pk_mul_f32 v[8:9], v[68:69], v[76:77] op_sel_hi:[1,0]
	v_lshl_add_u64 v[66:67], s[70:71], 0, v[78:79]
	s_and_saveexec_b64 s[18:19], s[6:7]
	s_cbranch_execz .LBB0_409
	v_lshl_add_u64 v[72:73], v[0:1], 3, v[66:67]
	global_load_dwordx4 v[68:71], v[72:73], off offset:16
	global_load_dwordx4 v[80:83], v[72:73], off
	s_waitcnt vmcnt(0)
	v_pk_mul_f32 v[72:73], v[2:3], v[80:81] op_sel:[1,1] op_sel_hi:[1,0]
	s_nop 0
	v_pk_fma_f32 v[78:79], v[2:3], v[80:81], v[72:73] op_sel_hi:[0,1,1] neg_lo:[0,0,1] neg_hi:[0,0,1]
	v_pk_fma_f32 v[2:3], v[2:3], v[80:81], v[72:73] op_sel_hi:[0,1,1]
	v_pk_mul_f32 v[72:73], v[4:5], v[82:83] op_sel:[1,1] op_sel_hi:[1,0]
	v_mul_f32_e32 v2, v9, v71
	v_pk_fma_f32 v[80:81], v[4:5], v[82:83], v[72:73] op_sel_hi:[0,1,1] neg_lo:[0,0,1] neg_hi:[0,0,1]
	v_pk_fma_f32 v[4:5], v[4:5], v[82:83], v[72:73] op_sel_hi:[0,1,1]
	v_pk_mul_f32 v[72:73], v[6:7], v[68:69] op_sel:[1,1] op_sel_hi:[1,0]
	v_pk_fma_f32 v[84:85], v[8:9], v[70:71], v[2:3] op_sel_hi:[1,1,0] neg_lo:[0,0,1] neg_hi:[0,0,1]
	v_mul_f32_e32 v2, v9, v70
	v_pk_fma_f32 v[82:83], v[6:7], v[68:69], v[72:73] op_sel_hi:[0,1,1] neg_lo:[0,0,1] neg_hi:[0,0,1]
	v_pk_fma_f32 v[6:7], v[6:7], v[68:69], v[72:73] op_sel_hi:[0,1,1]
	v_pk_fma_f32 v[8:9], v[8:9], v[70:71], v[2:3] op_sel:[0,1,0] op_sel_hi:[1,0,0]
	v_mov_b32_e32 v79, v3
	v_mov_b32_e32 v81, v5
	v_mov_b32_e32 v83, v7
	v_mov_b32_e32 v85, v8
	v_mov_b64_e32 v[2:3], v[78:79]
	v_mov_b64_e32 v[4:5], v[80:81]
	v_mov_b64_e32 v[6:7], v[82:83]
	v_mov_b64_e32 v[8:9], v[84:85]

; __device__ __forceinline__ float silu_f(float x) { return x * __builtin_amdgcn_rcpf(1.0f + __builtin_amdgcn_exp2f(-x * 1.4426950408889634f)); }
;     __device__ __forceinline__ void operator()(const f32x4 (&acc)[2][2][4][2], const Unit& u, int wr, int wc, int fr, int fq) const {
;     ...
;                 const int row = row0 + ai * HALF + m * 16;
;                 const float r = __builtin_amdgcn_rsqf(sum_parts<8>(ssq_h + (size_t)row * 32) * (1.0f / 2048.0f) + 1e-6f);
; #pragma unroll
;                 for (int bj = 0; bj < 2; ++bj) {
;                     float v[8];
; #pragma unroll
;                     for (int e = 0; e < 4; ++e) { v[e] = acc[ai][bj][m][0][e] * r; v[4 + e] = acc[ai][bj][m][1][e] * r; }
;                     if (tab[bj] >= 0) rope8(v, TAB + (size_t)row * NTAB + tab[bj]);
;                     if (act[bj]) {
; #pragma unroll
;                         for (int e = 0; e < 8; ++e) v[e] = silu_f(v[e]);
;                     }
; #pragma unroll
;                     for (int e = 0; e < 8; ++e) v[e] *= sc[bj];
;                     if (ssq[bj]) { float s = 0.f;
; #pragma unroll
;                         for (int e = 0; e < 8; ++e) s += v[e] * v[e];
;                         s += __shfl_xor(s, 16); s += __shfl_xor(s, 32);
;                         if (fq == 0) ssq[bj][(size_t)row * sld[bj]] = s; }
;                     store8(dst[bj] + (size_t)row * ld[bj], v);
.LBB0_423:
	v_mul_lo_u32 v7, s93, v74
	v_mul_lo_u32 v61, s92, v75
	s_waitcnt lgkmcnt(0)
	v_mad_u64_u32 v[8:9], s[18:19], s92, v74, 0
	v_add3_u32 v9, v9, v61, v7
	v_lshl_add_u64 v[8:9], v[8:9], 1, v[122:123]
	v_cvt_pk_bf16_f32 v58, v58, v60
	v_cvt_pk_bf16_f32 v59, v4, v59
	v_cvt_pk_bf16_f32 v60, v3, v5
	v_cvt_pk_bf16_f32 v61, v2, v6
	global_store_dwordx4 v[8:9], v[58:61], off
	s_nop 1
	v_add_u32_e32 v58, 0x90, v146
	v_ashrrev_i32_e32 v59, 31, v58
	v_mad_i64_i32 v[62:63], s[18:19], v58, s1, 0
	v_mov_b32_e32 v60, v173
	s_nop 0
	v_pk_mul_f32 v[2:3], v[54:55], v[60:61] op_sel_hi:[1,0]
	v_pk_mul_f32 v[6:7], v[50:51], v[60:61] op_sel_hi:[1,0]
	v_pk_mul_f32 v[4:5], v[56:57], v[60:61] op_sel_hi:[1,0]
	v_pk_mul_f32 v[8:9], v[52:53], v[60:61] op_sel_hi:[1,0]
	v_lshl_add_u64 v[50:51], s[70:71], 0, v[62:63]
	s_and_saveexec_b64 s[18:19], s[6:7]
	s_cbranch_execz .LBB0_425
	v_lshl_add_u64 v[56:57], v[0:1], 3, v[50:51]
	global_load_dwordx4 v[52:55], v[56:57], off offset:16
	global_load_dwordx4 v[64:67], v[56:57], off
	s_waitcnt vmcnt(0)
	v_pk_mul_f32 v[56:57], v[2:3], v[64:65] op_sel:[1,1] op_sel_hi:[1,0]
	s_nop 0
	v_pk_fma_f32 v[62:63], v[2:3], v[64:65], v[56:57] op_sel_hi:[0,1,1] neg_lo:[0,0,1] neg_hi:[0,0,1]
	v_pk_fma_f32 v[2:3], v[2:3], v[64:65], v[56:57] op_sel_hi:[0,1,1]
	v_pk_mul_f32 v[56:57], v[4:5], v[66:67] op_sel:[1,1] op_sel_hi:[1,0]
	v_mul_f32_e32 v2, v9, v55
	v_pk_fma_f32 v[64:65], v[4:5], v[66:67], v[56:57] op_sel_hi:[0,1,1] neg_lo:[0,0,1] neg_hi:[0,0,1]
	v_pk_fma_f32 v[4:5], v[4:5], v[66:67], v[56:57] op_sel_hi:[0,1,1]
	v_pk_mul_f32 v[56:57], v[6:7], v[52:53] op_sel:[1,1] op_sel_hi:[1,0]
	v_pk_fma_f32 v[68:69], v[8:9], v[54:55], v[2:3] op_sel_hi:[1,1,0] neg_lo:[0,0,1] neg_hi:[0,0,1]
	v_mul_f32_e32 v2, v9, v54
	v_pk_fma_f32 v[66:67], v[6:7], v[52:53], v[56:57] op_sel_hi:[0,1,1] neg_lo:[0,0,1] neg_hi:[0,0,1]
	v_pk_fma_f32 v[6:7], v[6:7], v[52:53], v[56:57] op_sel_hi:[0,1,1]
	v_pk_fma_f32 v[8:9], v[8:9], v[54:55], v[2:3] op_sel:[0,1,0] op_sel_hi:[1,0,0]
	v_mov_b32_e32 v63, v3
	v_mov_b32_e32 v65, v5
	v_mov_b32_e32 v67, v7
	v_mov_b32_e32 v69, v8
	v_mov_b64_e32 v[2:3], v[62:63]
	v_mov_b64_e32 v[4:5], v[64:65]
	v_mov_b64_e32 v[6:7], v[66:67]
	v_mov_b64_e32 v[8:9], v[68:69]

; __device__ __forceinline__ float silu_f(float x) { return x * __builtin_amdgcn_rcpf(1.0f + __builtin_amdgcn_exp2f(-x * 1.4426950408889634f)); }
;     __device__ __forceinline__ void operator()(const f32x4 (&acc)[2][2][4][2], const Unit& u, int wr, int wc, int fr, int fq) const {
;     ...
;                 const int row = row0 + ai * HALF + m * 16;
;                 const float r = __builtin_amdgcn_rsqf(sum_parts<8>(ssq_h + (size_t)row * 32) * (1.0f / 2048.0f) + 1e-6f);
; #pragma unroll
;                 for (int bj = 0; bj < 2; ++bj) {
;                     float v[8];
; #pragma unroll
;                     for (int e = 0; e < 4; ++e) { v[e] = acc[ai][bj][m][0][e] * r; v[4 + e] = acc[ai][bj][m][1][e] * r; }
;                     if (tab[bj] >= 0) rope8(v, TAB + (size_t)row * NTAB + tab[bj]);
;                     if (act[bj]) {
; #pragma unroll
;                         for (int e = 0; e < 8; ++e) v[e] = silu_f(v[e]);
;                     }
; #pragma unroll
;                     for (int e = 0; e < 8; ++e) v[e] *= sc[bj];
;                     if (ssq[bj]) { float s = 0.f;
; #pragma unroll
;                         for (int e = 0; e < 8; ++e) s += v[e] * v[e];
;                         s += __shfl_xor(s, 16); s += __shfl_xor(s, 32);
;                         if (fq == 0) ssq[bj][(size_t)row * sld[bj]] = s; }
;                     store8(dst[bj] + (size_t)row * ld[bj], v);
.LBB0_439:
	v_mul_lo_u32 v7, s93, v58
	v_mul_lo_u32 v45, s92, v59
	s_waitcnt lgkmcnt(0)
	v_mad_u64_u32 v[8:9], s[18:19], s92, v58, 0
	v_add3_u32 v9, v9, v45, v7
	v_lshl_add_u64 v[8:9], v[8:9], 1, v[122:123]
	v_cvt_pk_bf16_f32 v42, v42, v44
	v_cvt_pk_bf16_f32 v43, v4, v43
	v_cvt_pk_bf16_f32 v44, v3, v5
	v_cvt_pk_bf16_f32 v45, v2, v6
	global_store_dwordx4 v[8:9], v[42:45], off
	s_nop 1
	v_add_u32_e32 v42, 0xa0, v146
	v_ashrrev_i32_e32 v43, 31, v42
	v_mad_i64_i32 v[46:47], s[18:19], v42, s1, 0
	v_mov_b32_e32 v44, v174
	s_nop 0
	v_pk_mul_f32 v[2:3], v[38:39], v[44:45] op_sel_hi:[1,0]
	v_pk_mul_f32 v[6:7], v[34:35], v[44:45] op_sel_hi:[1,0]
	v_pk_mul_f32 v[4:5], v[40:41], v[44:45] op_sel_hi:[1,0]
	v_pk_mul_f32 v[8:9], v[36:37], v[44:45] op_sel_hi:[1,0]
	v_lshl_add_u64 v[34:35], s[70:71], 0, v[46:47]
	s_and_saveexec_b64 s[18:19], s[6:7]
	s_cbranch_execz .LBB0_441
	v_lshl_add_u64 v[40:41], v[0:1], 3, v[34:35]
	global_load_dwordx4 v[36:39], v[40:41], off offset:16
	global_load_dwordx4 v[48:51], v[40:41], off
	s_waitcnt vmcnt(0)
	v_pk_mul_f32 v[40:41], v[2:3], v[48:49] op_sel:[1,1] op_sel_hi:[1,0]
	s_nop 0
	v_pk_fma_f32 v[46:47], v[2:3], v[48:49], v[40:41] op_sel_hi:[0,1,1] neg_lo:[0,0,1] neg_hi:[0,0,1]
	v_pk_fma_f32 v[2:3], v[2:3], v[48:49], v[40:41] op_sel_hi:[0,1,1]
	v_pk_mul_f32 v[40:41], v[4:5], v[50:51] op_sel:[1,1] op_sel_hi:[1,0]
	v_mul_f32_e32 v2, v9, v39
	v_pk_fma_f32 v[48:49], v[4:5], v[50:51], v[40:41] op_sel_hi:[0,1,1] neg_lo:[0,0,1] neg_hi:[0,0,1]
	v_pk_fma_f32 v[4:5], v[4:5], v[50:51], v[40:41] op_sel_hi:[0,1,1]
	v_pk_mul_f32 v[40:41], v[6:7], v[36:37] op_sel:[1,1] op_sel_hi:[1,0]
	v_pk_fma_f32 v[52:53], v[8:9], v[38:39], v[2:3] op_sel_hi:[1,1,0] neg_lo:[0,0,1] neg_hi:[0,0,1]
	v_mul_f32_e32 v2, v9, v38
	v_pk_fma_f32 v[50:51], v[6:7], v[36:37], v[40:41] op_sel_hi:[0,1,1] neg_lo:[0,0,1] neg_hi:[0,0,1]
	v_pk_fma_f32 v[6:7], v[6:7], v[36:37], v[40:41] op_sel_hi:[0,1,1]
	v_pk_fma_f32 v[8:9], v[8:9], v[38:39], v[2:3] op_sel:[0,1,0] op_sel_hi:[1,0,0]
	v_mov_b32_e32 v47, v3
	v_mov_b32_e32 v49, v5
	v_mov_b32_e32 v51, v7
	v_mov_b32_e32 v53, v8
	v_mov_b64_e32 v[2:3], v[46:47]
	v_mov_b64_e32 v[4:5], v[48:49]
	v_mov_b64_e32 v[6:7], v[50:51]
	v_mov_b64_e32 v[8:9], v[52:53]

; __device__ __forceinline__ float silu_f(float x) { return x * __builtin_amdgcn_rcpf(1.0f + __builtin_amdgcn_exp2f(-x * 1.4426950408889634f)); }
;     __device__ __forceinline__ void operator()(const f32x4 (&acc)[2][2][4][2], const Unit& u, int wr, int wc, int fr, int fq) const {
;     ...
;                 const int row = row0 + ai * HALF + m * 16;
;                 const float r = __builtin_amdgcn_rsqf(sum_parts<8>(ssq_h + (size_t)row * 32) * (1.0f / 2048.0f) + 1e-6f);
; #pragma unroll
;                 for (int bj = 0; bj < 2; ++bj) {
;                     float v[8];
; #pragma unroll
;                     for (int e = 0; e < 4; ++e) { v[e] = acc[ai][bj][m][0][e] * r; v[4 + e] = acc[ai][bj][m][1][e] * r; }
;                     if (tab[bj] >= 0) rope8(v, TAB + (size_t)row * NTAB + tab[bj]);
;                     if (act[bj]) {
; #pragma unroll
;                         for (int e = 0; e < 8; ++e) v[e] = silu_f(v[e]);
;                     }
; #pragma unroll
;                     for (int e = 0; e < 8; ++e) v[e] *= sc[bj];
;                     if (ssq[bj]) { float s = 0.f;
; #pragma unroll
;                         for (int e = 0; e < 8; ++e) s += v[e] * v[e];
;                         s += __shfl_xor(s, 16); s += __shfl_xor(s, 32);
;                         if (fq == 0) ssq[bj][(size_t)row * sld[bj]] = s; }
;                     store8(dst[bj] + (size_t)row * ld[bj], v);
.LBB0_455:
	v_mul_lo_u32 v7, s93, v42
	v_mul_lo_u32 v29, s92, v43
	s_waitcnt lgkmcnt(0)
	v_mad_u64_u32 v[8:9], s[18:19], s92, v42, 0
	v_add3_u32 v9, v9, v29, v7
	v_lshl_add_u64 v[8:9], v[8:9], 1, v[122:123]
	v_cvt_pk_bf16_f32 v26, v26, v28
	v_cvt_pk_bf16_f32 v27, v4, v27
	v_cvt_pk_bf16_f32 v28, v3, v5
	v_cvt_pk_bf16_f32 v29, v2, v6
	global_store_dwordx4 v[8:9], v[26:29], off
	s_nop 1
	v_add_u32_e32 v26, 0xb0, v146
	v_ashrrev_i32_e32 v27, 31, v26
	v_mad_i64_i32 v[30:31], s[18:19], v26, s1, 0
	v_mov_b32_e32 v28, v175
	s_nop 0
	v_pk_mul_f32 v[2:3], v[22:23], v[28:29] op_sel_hi:[1,0]
	v_pk_mul_f32 v[6:7], v[18:19], v[28:29] op_sel_hi:[1,0]
	v_pk_mul_f32 v[4:5], v[24:25], v[28:29] op_sel_hi:[1,0]
	v_pk_mul_f32 v[8:9], v[20:21], v[28:29] op_sel_hi:[1,0]
	v_lshl_add_u64 v[18:19], s[70:71], 0, v[30:31]
	s_and_saveexec_b64 s[18:19], s[6:7]
	s_cbranch_execz .LBB0_457
	v_lshl_add_u64 v[24:25], v[0:1], 3, v[18:19]
	global_load_dwordx4 v[20:23], v[24:25], off offset:16
	global_load_dwordx4 v[32:35], v[24:25], off
	s_waitcnt vmcnt(1)
	v_mul_f32_e32 v0, v9, v23
	s_waitcnt vmcnt(0)
	v_pk_mul_f32 v[24:25], v[2:3], v[32:33] op_sel:[1,1] op_sel_hi:[1,0]
	v_pk_fma_f32 v[36:37], v[8:9], v[22:23], v[0:1] op_sel_hi:[1,1,0] neg_lo:[0,0,1] neg_hi:[0,0,1]
	v_pk_fma_f32 v[30:31], v[2:3], v[32:33], v[24:25] op_sel_hi:[0,1,1] neg_lo:[0,0,1] neg_hi:[0,0,1]
	v_pk_fma_f32 v[2:3], v[2:3], v[32:33], v[24:25] op_sel_hi:[0,1,1]
	v_pk_mul_f32 v[24:25], v[4:5], v[34:35] op_sel:[1,1] op_sel_hi:[1,0]
	v_mul_f32_e32 v0, v9, v22
	v_pk_fma_f32 v[32:33], v[4:5], v[34:35], v[24:25] op_sel_hi:[0,1,1] neg_lo:[0,0,1] neg_hi:[0,0,1]
	v_pk_fma_f32 v[4:5], v[4:5], v[34:35], v[24:25] op_sel_hi:[0,1,1]
	v_pk_mul_f32 v[24:25], v[6:7], v[20:21] op_sel:[1,1] op_sel_hi:[1,0]
	v_pk_fma_f32 v[8:9], v[8:9], v[22:23], v[0:1] op_sel:[0,1,0] op_sel_hi:[1,0,0]
	v_pk_fma_f32 v[34:35], v[6:7], v[20:21], v[24:25] op_sel_hi:[0,1,1] neg_lo:[0,0,1] neg_hi:[0,0,1]
	v_pk_fma_f32 v[6:7], v[6:7], v[20:21], v[24:25] op_sel_hi:[0,1,1]
	v_mov_b32_e32 v31, v3
	v_mov_b32_e32 v33, v5
	v_mov_b32_e32 v35, v7
	v_mov_b32_e32 v37, v8
	v_mov_b64_e32 v[2:3], v[30:31]
	v_mov_b64_e32 v[4:5], v[32:33]
	v_mov_b64_e32 v[6:7], v[34:35]
	v_mov_b64_e32 v[8:9], v[36:37]
